# layer 0: most of the weight prep moved from phase 0 into phase 2, done by workgroups 2..255 while workgroups 0 and 1 run the f32 side mixers
# speedup vs baseline: 1.0052x; 1.0052x over previous
.Lprep_chk:
	v_readlane_b32 s0, v254, 40
	v_readlane_b32 s1, v249, 25
	s_nop 0
	s_cmp_eq_u32 s0, 2
	s_cbranch_scc0 .LBB0_627
	s_cmp_lt_u32 s1, 16
	s_cbranch_scc1 .LBB0_627
	s_mov_b32 s32, 1
	s_barrier
	s_branch .Lprep_go

.LBB0_489:
	v_readlane_b32 s20, v254, 24
	s_and_b64 vcc, exec, s[0:1]
	v_readlane_b32 s21, v254, 25
	s_cbranch_vccz .Lprep_chk
	v_readlane_b32 s32, v254, 36
	s_nop 0
	s_cmp_eq_u32 s32, 0
	s_cselect_b32 s32, 2, 0
.Lprep_go:
	v_mov_b32_e32 v58, v216
	v_readlane_b32 s1, v249, 25
	v_readfirstlane_b32 s0, v58
	s_ashr_i32 s0, s0, 6
	s_add_i32 s6, s0, s1
	s_cmp_eq_u32 s32, 1
	s_cbranch_scc0 .Lprep_s6
	s_addk_i32 s6, 0x1070
.Lprep_s6:
	s_mov_b64 s[4:5], s[82:83]
	s_mov_b32 s44, 0x1c1000
	s_mov_b32 s37, 0x151000
	s_mov_b32 s45, 0xe0000
	s_cmpk_gt_i32 s6, 0x367f
	v_and_b32_e32 v57, 63, v58
	s_cbranch_scc1 .LBB0_605
	v_readlane_b32 s2, v254, 36
	v_readlane_b32 s8, v254, 8
	s_mov_b32 s24, s2
	s_ashr_i32 s25, s2, 31
	s_mul_hi_i32 s1, s2, 0x3830000
	s_mul_i32 s2, s2, 0x3830000
	v_readlane_b32 s14, v254, 14
	v_readlane_b32 s3, v254, 37
	v_readlane_b32 s10, v254, 10
	v_readlane_b32 s15, v254, 15
	v_readlane_b32 s16, v254, 16
	v_readlane_b32 s17, v254, 17
	v_readlane_b32 s18, v254, 18
	v_readlane_b32 s20, v254, 20
	v_readlane_b32 s21, v254, 21
	s_add_u32 s2, s14, s2
	s_mulk_i32 s0, 0x2200
	v_readlane_b32 s11, v254, 11
	v_readlane_b32 s19, v254, 19
	s_addc_u32 s3, s15, s1
	s_add_i32 s7, s0, 0
	s_lshl_b64 s[0:1], s[24:25], 24
	s_lshl_b32 s10, s24, 10
	s_lshl_b64 s[20:21], s[24:25], 22
	s_lshl_b64 s[16:17], s[24:25], 23
	s_lshl_b32 s18, s24, 11
	v_readlane_b32 s24, v253, 5
	s_ashr_i32 s11, s10, 31
	s_ashr_i32 s19, s18, 31
	v_readlane_b32 s26, v253, 7
	v_readlane_b32 s27, v253, 8
	s_add_u32 s38, s26, s0
	v_readlane_b32 s12, v254, 12
	v_readlane_b32 s13, v254, 13
	v_readlane_b32 s22, v254, 22
	v_readlane_b32 s23, v254, 23
	s_addc_u32 s39, s27, s1
	v_readlane_b32 s9, v254, 9
	v_readlane_b32 s25, v253, 6
	s_add_u32 s8, s24, s0
	s_mov_b64 s[12:13], s[62:63]
	s_mov_b64 s[22:23], s[60:61]
	v_readlane_b32 s48, v249, 38
	s_addc_u32 s9, s25, s1
	s_lshl_b64 s[0:1], s[10:11], 2
	v_readlane_b32 s62, v249, 52
	v_readlane_b32 s63, v249, 53
	s_add_u32 s10, s62, s0
	v_readlane_b32 s60, v249, 50
	s_addc_u32 s11, s63, s1
	v_readlane_b32 s61, v249, 51
	s_mov_b64 s[62:63], s[12:13]
	s_add_u32 s12, s60, s20
	v_readlane_b32 s58, v249, 48
	s_addc_u32 s13, s61, s21
	v_readlane_b32 s59, v249, 49
	s_add_u32 s14, s58, s20
	v_readlane_b32 s56, v249, 46
	s_addc_u32 s15, s59, s21
	v_readlane_b32 s57, v249, 47
	s_add_u32 s16, s56, s16
	v_readlane_b32 s68, v249, 56
	s_addc_u32 s17, s57, s17
	s_lshl_b64 s[18:19], s[18:19], 2
	v_readlane_b32 s78, v250, 2
	v_readlane_b32 s79, v250, 3
	s_add_u32 s18, s78, s18
	v_readlane_b32 s54, v249, 44
	v_readlane_b32 s69, v249, 57
	v_readlane_b32 s70, v249, 58
	v_readlane_b32 s71, v249, 59
	v_readlane_b32 s72, v249, 60
	v_readlane_b32 s73, v249, 61
	v_readlane_b32 s74, v249, 62
	v_readlane_b32 s75, v249, 63
	v_readlane_b32 s76, v250, 0
	v_readlane_b32 s77, v250, 1
	s_addc_u32 s19, s79, s19
	v_readlane_b32 s55, v249, 45
	v_readlane_b32 s64, v254, 8
	s_add_u32 s20, s54, s20
	v_readlane_b32 s68, v254, 12
	s_addc_u32 s21, s55, s21
	s_mov_b64 s[60:61], s[22:23]
	v_readlane_b32 s69, v254, 13
	s_add_u32 s22, s68, s0
	s_addc_u32 s23, s69, s1
	s_waitcnt lgkmcnt(0)
	v_and_b32_e32 v2, 7, v58
	v_readlane_b32 s0, v249, 26
	v_lshlrev_b32_e32 v0, 4, v2
	v_readlane_b32 s1, v249, 27
	v_lshrrev_b32_e32 v34, 3, v57
	v_readlane_b32 s28, v253, 9
	v_lshl_add_u64 v[36:37], s[0:1], 0, v[0:1]
	v_readlane_b32 s0, v252, 17
	v_readlane_b32 s1, v252, 18
	v_readlane_b32 s29, v253, 10
	v_readlane_b32 s42, v250, 10
	v_lshl_add_u64 v[38:39], s[0:1], 0, v[0:1]
	v_readlane_b32 s0, v249, 28
	v_readlane_b32 s1, v249, 29
	v_readlane_b32 s80, v250, 4
	v_readlane_b32 s81, v250, 5
	v_lshl_add_u64 v[40:41], s[0:1], 0, v[0:1]
	v_readlane_b32 s0, v249, 30
	v_readlane_b32 s1, v249, 31
	v_readlane_b32 s40, v250, 8
	v_mul_u32_u24_e32 v3, 0x420, v2
	v_lshl_add_u64 v[42:43], s[0:1], 0, v[0:1]
	v_readlane_b32 s0, v249, 32
	v_readlane_b32 s1, v249, 33
	v_lshlrev_b32_e32 v4, 2, v34
	v_lshlrev_b32_e32 v61, 2, v2
	v_lshl_add_u64 v[44:45], s[0:1], 0, v[0:1]
	v_readlane_b32 s0, v249, 34
	v_readlane_b32 s1, v249, 35
	v_or_b32_e32 v2, 32, v34
	s_mov_b32 s33, 0x70000
	v_lshl_add_u64 v[46:47], s[0:1], 0, v[0:1]
	v_readlane_b32 s0, v249, 36
	v_readlane_b32 s1, v249, 37
	v_readlane_b32 s43, v250, 11
	s_mov_b32 s80, 0x24000
	v_lshl_add_u64 v[48:49], s[0:1], 0, v[0:1]
	v_readlane_b32 s0, v249, 6
	v_readlane_b32 s1, v249, 7
	s_mov_b32 s81, 0xfc000
	v_readlane_b32 s41, v250, 9
	v_lshl_add_u64 v[50:51], s[0:1], 0, v[0:1]
	v_readlane_b32 s0, v254, 6
	s_cmp_eq_u32 s32, 1
	s_cselect_b32 s0, 0x7f0, s0
	v_add_u32_e32 v59, s7, v0
	v_add3_u32 v60, s7, v3, v4
	v_mul_u32_u24_e32 v62, 0x84, v34
	v_or_b32_e32 v63, 8, v34
	v_or_b32_e32 v64, 16, v34
	v_or_b32_e32 v65, 24, v34
	v_mul_u32_u24_e32 v66, 0x84, v2
	v_mov_b32_e32 v35, v1
	s_lshl_b32 s7, s6, 5
	s_lshl_b32 s26, s0, 5
	s_lshl_b32 s27, s6, 1
	s_lshl_b32 s28, s0, 1
	s_mov_b32 s29, s6
	v_readlane_b32 s30, v253, 11
	v_readlane_b32 s31, v253, 12
	v_readlane_b32 s49, v249, 39
	v_readlane_b32 s50, v249, 40
	v_readlane_b32 s51, v249, 41
	v_readlane_b32 s52, v249, 42
	v_readlane_b32 s53, v249, 43
	v_readlane_b32 s82, v250, 6
	v_readlane_b32 s83, v250, 7
	v_readlane_b32 s65, v254, 9
	v_readlane_b32 s66, v254, 10
	v_readlane_b32 s67, v254, 11
	v_readlane_b32 s70, v254, 14
	v_readlane_b32 s71, v254, 15
	v_readlane_b32 s72, v254, 16
	v_readlane_b32 s73, v254, 17
	v_readlane_b32 s74, v254, 18
	v_readlane_b32 s75, v254, 19
	v_readlane_b32 s76, v254, 20
	v_readlane_b32 s77, v254, 21
	v_readlane_b32 s78, v254, 22
	v_readlane_b32 s79, v254, 23
	v_readlane_b32 s1, v254, 7
	s_branch .LBB0_495

.LBB0_494:
	v_readlane_b32 s0, v254, 6
	s_cmp_eq_u32 s32, 1
	s_cselect_b32 s0, 0x7f0, s0
	s_add_i32 s29, s29, s0
	s_add_i32 s7, s7, s26
	s_add_i32 s27, s27, s28
	s_movk_i32 s0, 0x367f
	s_cmp_eq_u32 s32, 2
	s_cselect_b32 s0, 0x107f, s0
	s_cmp_gt_i32 s29, s0
	v_readlane_b32 s1, v254, 7
	s_cbranch_scc1 .LBB0_605

.LBB0_605:
	v_readlane_b32 s0, v252, 37
	s_waitcnt lgkmcnt(0)
	s_nop 0
	v_add_u32_e32 v2, s0, v58
	s_mov_b32 s0, 0x10000
	v_cmp_gt_i32_e32 vcc, s0, v2
	s_cmp_eq_u32 s32, 1
	s_cselect_b64 vcc, 0, vcc
	s_and_saveexec_b64 s[2:3], vcc
	v_readlane_b32 s20, v254, 24
	v_readlane_b32 s28, v254, 27
	v_readlane_b32 s10, v252, 63
	v_readlane_b32 s40, v254, 38
	v_readlane_b32 s21, v254, 25
	v_readlane_b32 s29, v254, 28
	v_readlane_b32 s11, v253, 0
	s_movk_i32 s26, 0x110
	s_mov_b32 s19, 0x400000
	s_mov_b64 s[82:83], s[4:5]
	v_readlane_b32 s41, v254, 39
	v_readlane_b32 s42, v254, 40
	v_readlane_b32 s43, v254, 41
	v_readlane_b32 s4, v254, 2
	v_readlane_b32 s5, v254, 3
	s_cbranch_execz .LBB0_613
	v_readlane_b32 s0, v252, 38
	s_mov_b64 s[8:9], -1
	s_nop 0
	v_add_u32_e32 v0, s0, v58
	s_mov_b32 s0, 0x10000
	v_max_i32_e32 v3, 0x10000, v0
	v_cmp_gt_i32_e64 s[0:1], s0, v0
	s_nop 1
	v_cndmask_b32_e64 v4, 1, 2, s[0:1]
	v_subb_co_u32_e64 v0, s[0:1], v3, v0, s[0:1]
	v_mul_hi_u32 v3, v0, v217
	v_mul_lo_u32 v5, v3, s4
	v_sub_u32_e32 v0, v0, v5
	v_add_u32_e32 v5, 1, v3
	v_cmp_le_u32_e64 s[0:1], s4, v0
	s_nop 1
	v_cndmask_b32_e64 v3, v3, v5, s[0:1]
	v_subrev_u32_e32 v5, s4, v0
	v_cndmask_b32_e64 v0, v0, v5, s[0:1]
	v_add_u32_e32 v5, 1, v3
	v_cmp_le_u32_e64 s[0:1], s4, v0
	s_nop 1
	v_cndmask_b32_e64 v0, v3, v5, s[0:1]
	v_add_u32_e32 v6, v4, v0
	v_cmp_lt_u32_e64 s[0:1], 1, v6
	v_mov_b32_e32 v4, v2
	s_and_saveexec_b64 s[4:5], s[0:1]
	s_cbranch_execz .LBB0_610
	v_readlane_b32 s0, v252, 32
	v_and_b32_e32 v7, -2, v6
	v_readlane_b32 s1, v252, 33
	v_readlane_b32 s14, v250, 12
	v_add_u32_e32 v0, s0, v2
	v_add_u32_e32 v3, s1, v2
	s_mov_b64 s[8:9], 0
	v_mov_b32_e32 v4, v7
	v_readlane_b32 s7, v253, 49
	v_readlane_b32 s12, v254, 29
	v_readlane_b32 s15, v250, 13

.LBB0_613:
	s_or_b64 exec, exec, s[2:3]
	s_cmp_eq_u32 s32, 1
	s_cbranch_scc1 .LBB0_627
	s_add_i32 s0, s42, 14
	s_cmp_gt_u32 s0, 28
	s_cbranch_scc1 .LBB0_627
	s_and_saveexec_b64 s[2:3], vcc
	v_readlane_b32 s4, v254, 2
	v_readlane_b32 s5, v254, 3
	s_cbranch_execz .LBB0_622
	v_readlane_b32 s0, v252, 38
	s_nop 1
	v_add_u32_e32 v0, s0, v58
	s_mov_b32 s0, 0x10000
	v_max_i32_e32 v3, 0x10000, v0
	v_cmp_gt_i32_e32 vcc, s0, v0
	s_mov_b64 s[0:1], -1
	s_nop 0
	v_cndmask_b32_e64 v4, 1, 2, vcc
	v_subb_co_u32_e32 v0, vcc, v3, v0, vcc
	v_mul_hi_u32 v3, v0, v217
	v_mul_lo_u32 v5, v3, s4
	v_sub_u32_e32 v0, v0, v5
	v_add_u32_e32 v5, 1, v3
	v_cmp_le_u32_e32 vcc, s4, v0
	s_nop 1
	v_cndmask_b32_e32 v3, v3, v5, vcc
	v_subrev_u32_e32 v5, s4, v0
	v_cndmask_b32_e32 v0, v0, v5, vcc
	v_add_u32_e32 v5, 1, v3
	v_cmp_le_u32_e32 vcc, s4, v0
	s_nop 1
	v_cndmask_b32_e32 v0, v3, v5, vcc
	v_add_u32_e32 v4, v4, v0
	v_cmp_lt_u32_e32 vcc, 1, v4
	s_and_saveexec_b64 s[4:5], vcc
	s_cbranch_execz .LBB0_619
	v_readlane_b32 s0, v252, 32
	v_and_b32_e32 v5, -2, v4
	v_readlane_b32 s1, v252, 33
	v_add_u32_e32 v0, s0, v2
	s_mov_b64 s[8:9], 0
	v_add_u32_e32 v3, s1, v2
	v_mov_b32_e32 v6, v5
	v_readlane_b32 s7, v253, 49
	v_readlane_b32 s12, v254, 29
